# pair8f plus sgu unit: stage-2 V and gain/bias loads issued ahead of the statistics pass, the 8 statistics loads issued as one batch
# baseline (speedup 1.0000x reference)
; #define LAS __attribute__((address_space(3)))
; __device__ __forceinline__ unsigned pk2(float lo, float hi) { return cvt_pk_bf16(lo, hi); }
; __device__ __forceinline__ void unit(const Frame& F, int c, int g, const bf16x8 (&af)[4][4]) {
;     ...
;     for (int cc = 0; cc < 4; ++cc) {
;         const int chunk = w * 4 + cc, r0 = 2 * lane;
;         const u32x4 x0 = *(const u32x4*)(F.V + (size_t)(tok0 + r0) * EA + ch0 + chunk * 8), x1 = *(const u32x4*)(F.V + (size_t)(tok0 + r0 + 1) * EA + ch0 + chunk * 8);
;         const f32x2 s0 = ST[r0], s1 = ST[r0 + 1];
;         const f32x4 ga = *(const f32x4*)(F.lnv_g + ch0 + chunk * 8), gb = *(const f32x4*)(F.lnv_g + ch0 + chunk * 8 + 4);
;         const f32x4 ba = *(const f32x4*)(F.lnv_b + ch0 + chunk * 8), bb = *(const f32x4*)(F.lnv_b + ch0 + chunk * 8 + 4);
;         const float gn[8] = {ga[0], ga[1], ga[2], ga[3], gb[0], gb[1], gb[2], gb[3]}, bs[8] = {ba[0], ba[1], ba[2], ba[3], bb[0], bb[1], bb[2], bb[3]};
;         const unsigned xa[4] = {x0.x, x0.y, x0.z, x0.w}, xb[4] = {x1.x, x1.y, x1.z, x1.w};
; #pragma unroll
;         for (int i = 0; i < 8; ++i) {
;             const float v0 = (i & 1) ? bfhi(xa[i >> 1]) : bflo(xa[i >> 1]), v1 = (i & 1) ? bfhi(xb[i >> 1]) : bflo(xb[i >> 1]);
;             const float n0 = (v0 - s0.x) * s0.y * gn[i] + bs[i], n1 = (v1 - s1.x) * s1.y * gn[i] + bs[i];
;             { const int chl = chunk * 8 + i;
;               const int slot = (chl & ~31) + 16 * ((chl >> 2) & 1) + 4 * ((chl >> 3) & 3) + (chl & 3);
;               *(LAS unsigned*)(lds + VT_OFF + slot * VT_STRIDE + lane * 4) = pk2(n0, n1); }
;         }
;     }
.LBB0_305:
	s_or_b64 exec, exec, s[62:63]
	v_and_b32_e32 v70, 63, v110
	v_lshl_or_b32 v64, v70, 1, s60
	v_ashrrev_i32_e32 v65, 31, v64
	s_and_b32 s61, s72, 7
	v_lshlrev_b64 v[66:67], 12, v[64:65]
	v_lshl_add_u64 v[66:67], s[76:77], 0, v[66:67]
	s_lshl_b32 s6, s61, 9
	s_lshl_b32 s50, s61, 10
	v_or_b32_e32 v64, 1, v64
	v_lshl_add_u64 v[66:67], v[66:67], 0, s[6:7]
	v_mov_b32_e32 v111, s50
	v_ashrrev_i32_e32 v65, 31, v64
	s_waitcnt lgkmcnt(0)
	s_barrier
	v_lshl_add_u64 v[68:69], v[66:67], 0, s[58:59]
	s_nop 0
	s_nop 0
	s_nop 0
	v_lshlrev_b64 v[64:65], 12, v[64:65]
	v_lshl_add_u64 v[64:65], s[76:77], 0, v[64:65]
	v_lshl_add_u64 v[64:65], v[64:65], 0, s[6:7]
	v_lshl_add_u64 v[76:77], v[64:65], 0, s[58:59]
	s_nop 0
	s_nop 0
	s_nop 0
	s_nop 0
	s_nop 0
	s_nop 0
	s_nop 0
	s_nop 0
	s_nop 0
	v_lshl_add_u32 v64, v70, 4, 0
	v_add_u32_e32 v152, 0x11000, v64
	ds_read_b128 v[136:139], v152
	v_lshl_add_u32 v115, v70, 2, 0
	v_add_u32_e32 v153, s1, v115
	v_add_u32_e32 v154, s3, v115
	v_add_u32_e32 v155, 0x1000, v153
	s_waitcnt lgkmcnt(0)
	v_mov_b32_e32 v112, v136
	v_mov_b32_e32 v113, v138
	v_mov_b32_e32 v138, v137
	global_load_dwordx4 v[64:67], v[68:69], off offset:48
	global_load_dwordx4 v[72:75], v[68:69], off offset:32
	s_nop 0
	global_load_dwordx4 v[68:71], v[76:77], off offset:48
	s_nop 0
	global_load_dwordx4 v[76:79], v[76:77], off offset:32
	s_add_i32 s72, s72, s34
	s_add_i32 s25, s25, s33
	s_add_i32 s35, s35, s64
	s_cmpk_lt_i32 s72, 0x600
	s_waitcnt vmcnt(15)
	v_mov_b32_e32 v108, v107
	s_waitcnt vmcnt(14)
	v_mov_b32_e32 v136, v119
	s_waitcnt vmcnt(13)
	v_lshlrev_b32_e32 v140, 16, v120
	v_and_b32_e32 v120, 0xffff0000, v120
	v_lshlrev_b32_e32 v142, 16, v121
	v_and_b32_e32 v144, 0xffff0000, v121
	s_waitcnt vmcnt(12)
	v_lshlrev_b32_e32 v141, 16, v124
	v_and_b32_e32 v121, 0xffff0000, v124
	v_lshlrev_b32_e32 v143, 16, v125
	v_lshlrev_b32_e32 v146, 16, v122
	v_and_b32_e32 v148, 0xffff0000, v122
	v_lshlrev_b32_e32 v150, 16, v123
	v_and_b32_e32 v145, 0xffff0000, v125
	v_lshlrev_b32_e32 v147, 16, v126
	v_and_b32_e32 v149, 0xffff0000, v126
	v_lshlrev_b32_e32 v151, 16, v127
	v_pk_add_f32 v[124:125], v[140:141], v[112:113] neg_lo:[0,1] neg_hi:[0,1]
	v_pk_add_f32 v[120:121], v[120:121], v[112:113] neg_lo:[0,1] neg_hi:[0,1]
	v_pk_add_f32 v[140:141], v[142:143], v[112:113] neg_lo:[0,1] neg_hi:[0,1]
	v_pk_add_f32 v[142:143], v[144:145], v[112:113] neg_lo:[0,1] neg_hi:[0,1]
	v_pk_add_f32 v[144:145], v[146:147], v[112:113] neg_lo:[0,1] neg_hi:[0,1]
	v_pk_add_f32 v[146:147], v[148:149], v[112:113] neg_lo:[0,1] neg_hi:[0,1]
	v_pk_add_f32 v[148:149], v[150:151], v[112:113] neg_lo:[0,1] neg_hi:[0,1]
	v_pk_mul_f32 v[124:125], v[138:139], v[124:125]
	v_pk_mul_f32 v[120:121], v[138:139], v[120:121]
	v_pk_mul_f32 v[140:141], v[138:139], v[140:141]
	v_pk_mul_f32 v[142:143], v[138:139], v[142:143]
	v_pk_mul_f32 v[144:145], v[138:139], v[144:145]
	v_pk_mul_f32 v[146:147], v[138:139], v[146:147]
	v_pk_mul_f32 v[148:149], v[138:139], v[148:149]
	v_pk_fma_f32 v[124:125], v[104:105], v[124:125], v[116:117] op_sel_hi:[0,1,0]
	v_pk_fma_f32 v[104:105], v[104:105], v[120:121], v[116:117] op_sel:[1,0,1]
	v_pk_fma_f32 v[106:107], v[106:107], v[140:141], v[118:119] op_sel_hi:[0,1,0]
	v_pk_fma_f32 v[116:117], v[108:109], v[142:143], v[136:137] op_sel_hi:[0,1,0]
	s_waitcnt vmcnt(10)
	v_pk_fma_f32 v[118:119], v[144:145], v[128:129], v[132:133] op_sel_hi:[1,0,0]
	v_pk_fma_f32 v[120:121], v[146:147], v[128:129], v[132:133] op_sel:[0,1,1]
	v_pk_fma_f32 v[128:129], v[148:149], v[130:131], v[134:135] op_sel_hi:[1,0,0]
	v_cvt_pk_bf16_f32 v108, v124, v125
	v_cvt_pk_bf16_f32 v104, v104, v105
	v_cvt_pk_bf16_f32 v105, v106, v107
	v_cvt_pk_bf16_f32 v106, v116, v117
	v_cvt_pk_bf16_f32 v107, v118, v119
	v_cvt_pk_bf16_f32 v116, v120, v121
	v_cvt_pk_bf16_f32 v117, v128, v129
	ds_write2_b32 v153, v108, v104 offset1:68
	ds_write2_b32 v153, v105, v106 offset0:136 offset1:204
	ds_write_b32 v154, v107
	ds_write2_b32 v155, v116, v117 offset0:132 offset1:200
	v_and_b32_e32 v105, 0xffff0000, v127
	v_and_b32_e32 v104, 0xffff0000, v123
	v_pk_add_f32 v[104:105], v[104:105], v[112:113] neg_lo:[0,1] neg_hi:[0,1]
	v_mov_b32_e32 v106, v131
	v_pk_mul_f32 v[104:105], v[138:139], v[104:105]
	v_mov_b32_e32 v108, v135
	v_pk_fma_f32 v[112:113], v[104:105], v[106:107], v[108:109] op_sel_hi:[1,0,0]
	global_load_dwordx4 v[104:107], v111, s[8:9] offset:64
	global_load_dwordx4 v[116:119], v111, s[22:23] offset:64
	v_cvt_pk_bf16_f32 v108, v112, v113
	ds_write_b32 v153, v108 offset:5168
	ds_read_b128 v[120:123], v152
	s_waitcnt vmcnt(11)
	v_lshlrev_b32_e32 v112, 16, v80
	s_waitcnt vmcnt(10)
	v_lshlrev_b32_e32 v113, 16, v84
	global_load_dwordx4 v[124:127], v111, s[8:9] offset:80
	global_load_dwordx4 v[128:131], v111, s[22:23] offset:80
	s_waitcnt lgkmcnt(0)
	v_mov_b32_e32 v132, v120
	v_mov_b32_e32 v133, v122
	v_pk_add_f32 v[112:113], v[112:113], v[132:133] neg_lo:[0,1] neg_hi:[0,1]
	v_mov_b32_e32 v122, v121
	v_pk_mul_f32 v[112:113], v[122:123], v[112:113]
	s_waitcnt vmcnt(8)
; #define LAS __attribute__((address_space(3)))
; __device__ __forceinline__ unsigned pk2(float lo, float hi) { return cvt_pk_bf16(lo, hi); }
; __device__ __forceinline__ void unit(const Frame& F, int c, int g, const bf16x8 (&af)[4][4]) {
;     ...
;     for (int cc = 0; cc < 4; ++cc) {
;         const int chunk = w * 4 + cc, r0 = 2 * lane;
;         const u32x4 x0 = *(const u32x4*)(F.V + (size_t)(tok0 + r0) * EA + ch0 + chunk * 8), x1 = *(const u32x4*)(F.V + (size_t)(tok0 + r0 + 1) * EA + ch0 + chunk * 8);
;         const f32x2 s0 = ST[r0], s1 = ST[r0 + 1];
;         const f32x4 ga = *(const f32x4*)(F.lnv_g + ch0 + chunk * 8), gb = *(const f32x4*)(F.lnv_g + ch0 + chunk * 8 + 4);
;         const f32x4 ba = *(const f32x4*)(F.lnv_b + ch0 + chunk * 8), bb = *(const f32x4*)(F.lnv_b + ch0 + chunk * 8 + 4);
;         const float gn[8] = {ga[0], ga[1], ga[2], ga[3], gb[0], gb[1], gb[2], gb[3]}, bs[8] = {ba[0], ba[1], ba[2], ba[3], bb[0], bb[1], bb[2], bb[3]};
;         const unsigned xa[4] = {x0.x, x0.y, x0.z, x0.w}, xb[4] = {x1.x, x1.y, x1.z, x1.w};
; #pragma unroll
;         for (int i = 0; i < 8; ++i) {
;             const float v0 = (i & 1) ? bfhi(xa[i >> 1]) : bflo(xa[i >> 1]), v1 = (i & 1) ? bfhi(xb[i >> 1]) : bflo(xb[i >> 1]);
;             const float n0 = (v0 - s0.x) * s0.y * gn[i] + bs[i], n1 = (v1 - s1.x) * s1.y * gn[i] + bs[i];
;             { const int chl = chunk * 8 + i;
;               const int slot = (chl & ~31) + 16 * ((chl >> 2) & 1) + 4 * ((chl >> 3) & 3) + (chl & 3);
;               *(LAS unsigned*)(lds + VT_OFF + slot * VT_STRIDE + lane * 4) = pk2(n0, n1); }
;         }
;     }
	v_pk_fma_f32 v[112:113], v[96:97], v[112:113], v[100:101] op_sel_hi:[0,1,0]
	v_cvt_pk_bf16_f32 v108, v112, v113
	v_and_b32_e32 v113, 0xffff0000, v84
	v_and_b32_e32 v112, 0xffff0000, v80
	v_pk_add_f32 v[112:113], v[112:113], v[132:133] neg_lo:[0,1] neg_hi:[0,1]
	v_and_b32_e32 v84, 0xffff0000, v81
	v_pk_mul_f32 v[112:113], v[122:123], v[112:113]
	s_nop 0
	v_pk_fma_f32 v[96:97], v[96:97], v[112:113], v[100:101] op_sel:[1,0,1]
	v_add_u32_e32 v100, 0x400, v153
	v_cvt_pk_bf16_f32 v80, v96, v97
	v_lshlrev_b32_e32 v96, 16, v81
	v_lshlrev_b32_e32 v97, 16, v85
	v_pk_add_f32 v[96:97], v[96:97], v[132:133] neg_lo:[0,1] neg_hi:[0,1]
	v_and_b32_e32 v85, 0xffff0000, v85
	v_pk_mul_f32 v[96:97], v[122:123], v[96:97]
	ds_write2_b32 v100, v108, v80 offset0:16 offset1:84
	v_pk_fma_f32 v[96:97], v[98:99], v[96:97], v[102:103] op_sel_hi:[0,1,0]
	v_pk_add_f32 v[80:81], v[84:85], v[132:133] neg_lo:[0,1] neg_hi:[0,1]
	v_cvt_pk_bf16_f32 v97, v96, v97
	v_pk_mul_f32 v[80:81], v[122:123], v[80:81]
	v_mov_b32_e32 v84, v99
	v_mov_b32_e32 v96, v103
	v_pk_fma_f32 v[80:81], v[84:85], v[80:81], v[96:97] op_sel_hi:[0,1,0]
	v_cvt_pk_bf16_f32 v80, v80, v81
	ds_write2_b32 v100, v97, v80 offset0:152 offset1:220
	v_lshlrev_b32_e32 v80, 16, v82
	v_lshlrev_b32_e32 v81, 16, v86
	v_pk_add_f32 v[80:81], v[80:81], v[132:133] neg_lo:[0,1] neg_hi:[0,1]
	s_waitcnt vmcnt(6)
	v_lshlrev_b32_e32 v100, 16, v72
	v_pk_mul_f32 v[80:81], v[122:123], v[80:81]
	s_waitcnt vmcnt(4)
	v_lshlrev_b32_e32 v101, 16, v76
	v_pk_fma_f32 v[80:81], v[80:81], v[88:89], v[92:93] op_sel_hi:[1,0,0]
	v_and_b32_e32 v108, 15, v110
	v_cvt_pk_bf16_f32 v84, v80, v81
	v_and_b32_e32 v81, 0xffff0000, v86
	v_and_b32_e32 v80, 0xffff0000, v82
	v_pk_add_f32 v[80:81], v[80:81], v[132:133] neg_lo:[0,1] neg_hi:[0,1]
	v_mov_b32_e32 v82, v91
	v_pk_mul_f32 v[80:81], v[122:123], v[80:81]
	v_or_b32_e32 v112, s0, v108
	v_pk_fma_f32 v[80:81], v[80:81], v[88:89], v[92:93] op_sel:[0,1,1]
	s_nop 0
	v_cvt_pk_bf16_f32 v80, v80, v81
	v_add_u32_e32 v81, 0x1400, v153
	ds_write2_b32 v81, v84, v80 offset0:80 offset1:148
	v_lshlrev_b32_e32 v80, 16, v83
	v_lshlrev_b32_e32 v81, 16, v87
	v_pk_add_f32 v[80:81], v[80:81], v[132:133] neg_lo:[0,1] neg_hi:[0,1]
	v_mov_b32_e32 v84, v95
	v_pk_mul_f32 v[80:81], v[122:123], v[80:81]
	s_nop 0
	v_pk_fma_f32 v[80:81], v[80:81], v[90:91], v[94:95] op_sel_hi:[1,0,0]
	v_add_u32_e32 v90, 0x1600, v153
	v_cvt_pk_bf16_f32 v88, v80, v81
	v_and_b32_e32 v81, 0xffff0000, v87
	v_and_b32_e32 v80, 0xffff0000, v83
	v_pk_add_f32 v[80:81], v[80:81], v[132:133] neg_lo:[0,1] neg_hi:[0,1]
	s_nop 0
	v_pk_mul_f32 v[80:81], v[122:123], v[80:81]
	s_nop 0
	v_pk_fma_f32 v[80:81], v[80:81], v[82:83], v[84:85] op_sel_hi:[1,0,0]
	s_nop 0
	v_cvt_pk_bf16_f32 v89, v80, v81
	global_load_dwordx4 v[80:83], v111, s[8:9] offset:96
	global_load_dwordx4 v[84:87], v111, s[22:23] offset:96
	ds_write2_b32 v90, v88, v89 offset0:88 offset1:156
	ds_read_b128 v[88:91], v152
	global_load_dwordx4 v[92:95], v111, s[8:9] offset:112
	global_load_dwordx4 v[96:99], v111, s[22:23] offset:112
	s_waitcnt lgkmcnt(0)
	v_mov_b32_e32 v102, v88
	v_mov_b32_e32 v103, v90
	v_pk_add_f32 v[100:101], v[100:101], v[102:103] neg_lo:[0,1] neg_hi:[0,1]
	v_mov_b32_e32 v90, v89
	v_pk_mul_f32 v[88:89], v[90:91], v[100:101]
	s_waitcnt vmcnt(6)
	v_pk_fma_f32 v[88:89], v[104:105], v[88:89], v[116:117] op_sel_hi:[0,1,0]
	v_cvt_pk_bf16_f32 v88, v88, v89
	v_add_u32_e32 v89, s10, v115
	ds_write_b32 v89, v88
	v_and_b32_e32 v89, 0xffff0000, v76
	v_and_b32_e32 v88, 0xffff0000, v72
	v_pk_add_f32 v[88:89], v[88:89], v[102:103] neg_lo:[0,1] neg_hi:[0,1]
	s_nop 0
	v_pk_mul_f32 v[88:89], v[90:91], v[88:89]
	s_nop 0
	v_pk_fma_f32 v[88:89], v[104:105], v[88:89], v[116:117] op_sel:[1,0,1]
	s_nop 0
	v_cvt_pk_bf16_f32 v72, v88, v89
	v_lshlrev_b32_e32 v88, 16, v73
	v_lshlrev_b32_e32 v89, 16, v77
	v_pk_add_f32 v[88:89], v[88:89], v[102:103] neg_lo:[0,1] neg_hi:[0,1]
	v_and_b32_e32 v77, 0xffff0000, v77
	v_pk_mul_f32 v[88:89], v[90:91], v[88:89]
	s_nop 0
	v_pk_fma_f32 v[88:89], v[106:107], v[88:89], v[118:119] op_sel_hi:[0,1,0]
	v_cvt_pk_bf16_f32 v76, v88, v89
	v_add_u32_e32 v88, 0x800, v153
	ds_write2_b32 v88, v72, v76 offset0:100 offset1:168
	v_and_b32_e32 v76, 0xffff0000, v73
	v_pk_add_f32 v[72:73], v[76:77], v[102:103] neg_lo:[0,1] neg_hi:[0,1]
	v_mov_b32_e32 v76, v107
	v_pk_mul_f32 v[72:73], v[90:91], v[72:73]
	v_mov_b32_e32 v88, v119
	v_pk_fma_f32 v[72:73], v[76:77], v[72:73], v[88:89] op_sel_hi:[0,1,0]
	v_cvt_pk_bf16_f32 v72, v72, v73
	ds_write_b32 v153, v72 offset:2992
	v_lshlrev_b32_e32 v72, 16, v74
	v_lshlrev_b32_e32 v73, 16, v78
	v_pk_add_f32 v[72:73], v[72:73], v[102:103] neg_lo:[0,1] neg_hi:[0,1]
	s_waitcnt vmcnt(4)
	v_mov_b32_e32 v76, v131
	v_pk_mul_f32 v[72:73], v[90:91], v[72:73]
	s_nop 0
	v_pk_fma_f32 v[72:73], v[72:73], v[124:125], v[128:129] op_sel_hi:[1,0,0]
	s_nop 0
	v_cvt_pk_bf16_f32 v72, v72, v73
	ds_write_b32 v154, v72 offset:2176
	v_and_b32_e32 v73, 0xffff0000, v78
	v_and_b32_e32 v72, 0xffff0000, v74
	v_pk_add_f32 v[72:73], v[72:73], v[102:103] neg_lo:[0,1] neg_hi:[0,1]
	s_nop 0
	v_pk_mul_f32 v[72:73], v[90:91], v[72:73]
	s_nop 0
	v_pk_fma_f32 v[72:73], v[72:73], v[124:125], v[128:129] op_sel:[0,1,1]
	s_nop 0
	v_cvt_pk_bf16_f32 v74, v72, v73
	v_lshlrev_b32_e32 v72, 16, v75
	v_lshlrev_b32_e32 v73, 16, v79
	v_pk_add_f32 v[72:73], v[72:73], v[102:103] neg_lo:[0,1] neg_hi:[0,1]
	s_nop 0
	v_pk_mul_f32 v[72:73], v[90:91], v[72:73]
	s_nop 0
	v_pk_fma_f32 v[72:73], v[72:73], v[126:127], v[130:131] op_sel_hi:[1,0,0]
	s_nop 0
	v_cvt_pk_bf16_f32 v72, v72, v73
	v_add_u32_e32 v73, 0x1800, v153
	ds_write2_b32 v73, v74, v72 offset0:164 offset1:232
	v_and_b32_e32 v73, 0xffff0000, v79
	v_and_b32_e32 v72, 0xffff0000, v75
	v_pk_add_f32 v[72:73], v[72:73], v[102:103] neg_lo:[0,1] neg_hi:[0,1]
	v_mov_b32_e32 v74, v127
	v_pk_mul_f32 v[72:73], v[90:91], v[72:73]
	s_nop 0
	v_pk_fma_f32 v[72:73], v[72:73], v[74:75], v[76:77] op_sel_hi:[1,0,0]
	v_lshlrev_b32_e32 v76, 16, v64
	v_cvt_pk_bf16_f32 v72, v72, v73
	ds_write_b32 v153, v72 offset:7344
	ds_read_b128 v[72:75], v152
	v_lshlrev_b32_e32 v77, 16, v68
	s_waitcnt lgkmcnt(0)
; #define LAS __attribute__((address_space(3)))
; __device__ __forceinline__ unsigned pk2(float lo, float hi) { return cvt_pk_bf16(lo, hi); }
; __device__ __forceinline__ void unit(const Frame& F, int c, int g, const bf16x8 (&af)[4][4]) {
;     ...
;     for (int cc = 0; cc < 4; ++cc) {
;         const int chunk = w * 4 + cc, r0 = 2 * lane;
;         const u32x4 x0 = *(const u32x4*)(F.V + (size_t)(tok0 + r0) * EA + ch0 + chunk * 8), x1 = *(const u32x4*)(F.V + (size_t)(tok0 + r0 + 1) * EA + ch0 + chunk * 8);
;         const f32x2 s0 = ST[r0], s1 = ST[r0 + 1];
;         const f32x4 ga = *(const f32x4*)(F.lnv_g + ch0 + chunk * 8), gb = *(const f32x4*)(F.lnv_g + ch0 + chunk * 8 + 4);
;         const f32x4 ba = *(const f32x4*)(F.lnv_b + ch0 + chunk * 8), bb = *(const f32x4*)(F.lnv_b + ch0 + chunk * 8 + 4);
;         const float gn[8] = {ga[0], ga[1], ga[2], ga[3], gb[0], gb[1], gb[2], gb[3]}, bs[8] = {ba[0], ba[1], ba[2], ba[3], bb[0], bb[1], bb[2], bb[3]};
;         const unsigned xa[4] = {x0.x, x0.y, x0.z, x0.w}, xb[4] = {x1.x, x1.y, x1.z, x1.w};
; #pragma unroll
;         for (int i = 0; i < 8; ++i) {
;             const float v0 = (i & 1) ? bfhi(xa[i >> 1]) : bflo(xa[i >> 1]), v1 = (i & 1) ? bfhi(xb[i >> 1]) : bflo(xb[i >> 1]);
;             const float n0 = (v0 - s0.x) * s0.y * gn[i] + bs[i], n1 = (v1 - s1.x) * s1.y * gn[i] + bs[i];
;             { const int chl = chunk * 8 + i;
;               const int slot = (chl & ~31) + 16 * ((chl >> 2) & 1) + 4 * ((chl >> 3) & 3) + (chl & 3);
;               *(LAS unsigned*)(lds + VT_OFF + slot * VT_STRIDE + lane * 4) = pk2(n0, n1); }
;         }
;     }
;     __syncthreads();
;     f32x4 acc[4][4];
; #pragma unroll
;     for (int m = 0; m < 4; ++m)
; #pragma unroll
;         for (int n = 0; n < 4; ++n) acc[m][n] = (f32x4){0.f, 0.f, 0.f, 0.f};
; #pragma unroll
;     for (int ks = 0; ks < 4; ++ks) {
;         bf16x8 bfm[4];
; #pragma unroll
;         for (int n = 0; n < 4; ++n) bfm[n] = *(const LAS bf16x8*)(lds + VT_OFF + (wc * 64 + n * 16 + fr) * VT_STRIDE + ks * 64 + fq * 16);
; #pragma unroll
;         for (int m = 0; m < 4; ++m)
; #pragma unroll
;             for (int n = 0; n < 4; ++n) acc[m][n] = __builtin_amdgcn_mfma_f32_16x16x32_bf16(bfm[n], af[m][ks], acc[m][n], 0, 0, 0);
	v_mov_b32_e32 v78, v72
	v_mov_b32_e32 v79, v74
	v_pk_add_f32 v[76:77], v[76:77], v[78:79] neg_lo:[0,1] neg_hi:[0,1]
	v_mov_b32_e32 v74, v73
	v_pk_mul_f32 v[72:73], v[74:75], v[76:77]
	v_add_u32_e32 v77, 0xc00, v153
	s_waitcnt vmcnt(2)
	v_pk_fma_f32 v[72:73], v[80:81], v[72:73], v[84:85] op_sel_hi:[0,1,0]
	v_cvt_pk_bf16_f32 v76, v72, v73
	v_and_b32_e32 v73, 0xffff0000, v68
	v_and_b32_e32 v72, 0xffff0000, v64
	v_pk_add_f32 v[72:73], v[72:73], v[78:79] neg_lo:[0,1] neg_hi:[0,1]
	v_and_b32_e32 v68, 0xffff0000, v65
	v_pk_mul_f32 v[72:73], v[74:75], v[72:73]
	s_nop 0
	v_pk_fma_f32 v[72:73], v[80:81], v[72:73], v[84:85] op_sel:[1,0,1]
	s_nop 0
	v_cvt_pk_bf16_f32 v64, v72, v73
	v_lshlrev_b32_e32 v72, 16, v65
	v_lshlrev_b32_e32 v73, 16, v69
	v_pk_add_f32 v[72:73], v[72:73], v[78:79] neg_lo:[0,1] neg_hi:[0,1]
	v_and_b32_e32 v69, 0xffff0000, v69
	v_pk_mul_f32 v[72:73], v[74:75], v[72:73]
	ds_write2_b32 v77, v76, v64 offset0:48 offset1:116
	v_pk_fma_f32 v[72:73], v[82:83], v[72:73], v[86:87] op_sel_hi:[0,1,0]
	v_pk_add_f32 v[64:65], v[68:69], v[78:79] neg_lo:[0,1] neg_hi:[0,1]
	v_cvt_pk_bf16_f32 v73, v72, v73
	v_pk_mul_f32 v[64:65], v[74:75], v[64:65]
	v_mov_b32_e32 v68, v83
	v_mov_b32_e32 v72, v87
	v_pk_fma_f32 v[64:65], v[68:69], v[64:65], v[72:73] op_sel_hi:[0,1,0]
	v_cvt_pk_bf16_f32 v64, v64, v65
	ds_write2_b32 v77, v73, v64 offset0:184 offset1:252
	v_lshlrev_b32_e32 v64, 16, v66
	v_lshlrev_b32_e32 v65, 16, v70
	v_pk_add_f32 v[64:65], v[64:65], v[78:79] neg_lo:[0,1] neg_hi:[0,1]
	s_nop 0
	v_pk_mul_f32 v[64:65], v[74:75], v[64:65]
	s_waitcnt vmcnt(0)
	v_pk_fma_f32 v[64:65], v[64:65], v[92:93], v[96:97] op_sel_hi:[1,0,0]
	s_nop 0
	v_cvt_pk_bf16_f32 v68, v64, v65
	v_and_b32_e32 v65, 0xffff0000, v70
	v_and_b32_e32 v64, 0xffff0000, v66
	v_pk_add_f32 v[64:65], v[64:65], v[78:79] neg_lo:[0,1] neg_hi:[0,1]
	v_mov_b32_e32 v66, v95
	v_pk_mul_f32 v[64:65], v[74:75], v[64:65]
	s_nop 0
	v_pk_fma_f32 v[64:65], v[64:65], v[92:93], v[96:97] op_sel:[0,1,1]
	s_nop 0
	v_cvt_pk_bf16_f32 v64, v64, v65
	v_add_u32_e32 v65, 0x1c00, v153
	ds_write2_b32 v65, v68, v64 offset0:112 offset1:180
	v_lshlrev_b32_e32 v64, 16, v67
	v_lshlrev_b32_e32 v65, 16, v71
	v_pk_add_f32 v[64:65], v[64:65], v[78:79] neg_lo:[0,1] neg_hi:[0,1]
	v_mov_b32_e32 v68, v99
	v_pk_mul_f32 v[64:65], v[74:75], v[64:65]
	s_nop 0
	v_pk_fma_f32 v[64:65], v[64:65], v[94:95], v[98:99] op_sel_hi:[1,0,0]
	s_nop 0
	v_cvt_pk_bf16_f32 v69, v64, v65
	v_and_b32_e32 v65, 0xffff0000, v71
	v_and_b32_e32 v64, 0xffff0000, v67
	v_pk_add_f32 v[64:65], v[64:65], v[78:79] neg_lo:[0,1] neg_hi:[0,1]
	s_nop 0
	v_pk_mul_f32 v[64:65], v[74:75], v[64:65]
	s_nop 0
	v_pk_fma_f32 v[64:65], v[64:65], v[66:67], v[68:69] op_sel_hi:[1,0,0]
	s_nop 0
	v_cvt_pk_bf16_f32 v64, v64, v65
	v_add_u32_e32 v65, 0x1e00, v153
	ds_write2_b32 v65, v69, v64 offset0:120 offset1:188
	v_or_b32_e32 v64, s11, v108
	v_and_b32_e32 v65, 48, v110
	v_mul_u32_u24_e32 v64, 0x110, v64
	v_add3_u32 v111, 0, v65, v64
	s_waitcnt lgkmcnt(0)
	s_barrier
	v_lshrrev_b32_e32 v220, 1, v110
	v_and_or_b32 v221, v220, 24, s11
	v_lshl_or_b32 v221, v221, 1, s6
	v_add_u32_e32 v222, s60, v112
	v_lshl_or_b32 v224, v222, 12, v221
	v_add_u32_e32 v223, 16, v222
	v_lshl_or_b32 v225, v223, 12, v221
	v_add_u32_e32 v223, 32, v222
	v_lshl_or_b32 v226, v223, 12, v221
	v_add_u32_e32 v223, 48, v222
	v_lshl_or_b32 v227, v223, 12, v221
	v_lshl_add_u32 v228, s61, 7, v112
	v_lshlrev_b32_e32 v228, 2, v228
	global_load_dwordx4 v[184:187], v224, s[26:27]
	global_load_dwordx4 v[188:191], v224, s[26:27] offset:64
	global_load_dwordx4 v[192:195], v225, s[26:27]
	global_load_dwordx4 v[196:199], v225, s[26:27] offset:64
	global_load_dwordx4 v[200:203], v226, s[26:27]
	global_load_dwordx4 v[204:207], v226, s[26:27] offset:64
	global_load_dwordx4 v[208:211], v227, s[26:27]
	global_load_dwordx4 v[212:215], v227, s[26:27] offset:64
	global_load_dword v216, v228, s[20:21]
	global_load_dword v217, v228, s[20:21] offset:64
	global_load_dword v218, v228, s[20:21] offset:128
	global_load_dword v219, v228, s[20:21] offset:192
	ds_read_b128 v[64:67], v111
	ds_read_b128 v[68:71], v111 offset:64
	ds_read_b128 v[76:79], v111 offset:4352
	ds_read_b128 v[80:83], v111 offset:4416
	ds_read_b128 v[88:91], v111 offset:8704
	ds_read_b128 v[92:95], v111 offset:8768
	s_waitcnt lgkmcnt(5)
	v_mfma_f32_16x16x32_bf16 v[72:75], v[64:67], v[0:3], 0
	ds_read_b128 v[100:103], v111 offset:13056
	ds_read_b128 v[104:107], v111 offset:13120
	v_lshrrev_b32_e32 v110, 1, v110
	v_lshl_add_u32 v108, s61, 7, v112
	s_waitcnt lgkmcnt(3)
	v_mfma_f32_16x16x32_bf16 v[96:99], v[88:91], v[0:3], 0
	v_add_u32_e32 v112, s60, v112
	v_and_or_b32 v115, v110, 24, s11
	v_ashrrev_i32_e32 v113, 31, v112
	v_mfma_f32_16x16x32_bf16 v[128:131], v[88:91], v[16:19], 0
	v_lshl_or_b32 v115, v115, 1, s6
	v_mfma_f32_16x16x32_bf16 v[144:147], v[88:91], v[32:35], 0
	v_mfma_f32_16x16x32_bf16 v[88:91], v[88:91], v[48:51], 0
	v_mfma_f32_16x16x32_bf16 v[84:87], v[76:79], v[0:3], 0
	v_mfma_f32_16x16x32_bf16 v[120:123], v[64:67], v[16:19], 0
	v_mfma_f32_16x16x32_bf16 v[124:127], v[76:79], v[16:19], 0
	v_mfma_f32_16x16x32_bf16 v[136:139], v[64:67], v[32:35], 0
	v_mfma_f32_16x16x32_bf16 v[140:143], v[76:79], v[32:35], 0
	v_mfma_f32_16x16x32_bf16 v[64:67], v[64:67], v[48:51], 0
	v_mfma_f32_16x16x32_bf16 v[76:79], v[76:79], v[48:51], 0
	v_mfma_f32_16x16x32_bf16 v[72:75], v[68:71], v[4:7], v[72:75]
	s_waitcnt lgkmcnt(2)
; #define LAS __attribute__((address_space(3)))
; __device__ __forceinline__ unsigned pk2(float lo, float hi) { return cvt_pk_bf16(lo, hi); }
; __device__ __forceinline__ void unit(const Frame& F, int c, int g, const bf16x8 (&af)[4][4]) {
;     ...
; #pragma unroll
;     for (int ks = 0; ks < 4; ++ks) {
;         bf16x8 bfm[4];
; #pragma unroll
;         for (int n = 0; n < 4; ++n) bfm[n] = *(const LAS bf16x8*)(lds + VT_OFF + (wc * 64 + n * 16 + fr) * VT_STRIDE + ks * 64 + fq * 16);
; #pragma unroll
;         for (int m = 0; m < 4; ++m)
; #pragma unroll
;             for (int n = 0; n < 4; ++n) acc[m][n] = __builtin_amdgcn_mfma_f32_16x16x32_bf16(bfm[n], af[m][ks], acc[m][n], 0, 0, 0);
;     }
; #pragma unroll
;     for (int m = 0; m < 4; ++m) {
;         const int p = wr * 64 + m * 16 + fr; const float bsp = F.b_sp[g * 128 + p];
;         const size_t rowoff = (size_t)(tok0 + p) * EA + ch0 + wc * 64 + 8 * fq;
; #pragma unroll
;         for (int h2 = 0; h2 < 2; ++h2) {
;             const u32x4 uu = *(const u32x4*)(F.U + rowoff + h2 * 32);
;             const f32x4 s0 = acc[m][2 * h2] + bsp, s1 = acc[m][2 * h2 + 1] + bsp;
;             u32x4 o;
;             o.x = pk2(bflo(uu.x) * s0[0], bfhi(uu.x) * s0[1]); o.y = pk2(bflo(uu.y) * s0[2], bfhi(uu.y) * s0[3]);
;             o.z = pk2(bflo(uu.z) * s1[0], bfhi(uu.z) * s1[1]); o.w = pk2(bflo(uu.w) * s1[2], bfhi(uu.w) * s1[3]);
;             *(u32x4*)(F.ABUF + rowoff + h2 * 32) = o;
	v_mfma_f32_16x16x32_bf16 v[96:99], v[92:95], v[4:7], v[96:99]
	v_mfma_f32_16x16x32_bf16 v[128:131], v[92:95], v[20:23], v[128:131]
	v_mfma_f32_16x16x32_bf16 v[144:147], v[92:95], v[36:39], v[144:147]
	v_mfma_f32_16x16x32_bf16 v[156:159], v[92:95], v[52:55], v[88:91]
	ds_read_b128 v[92:95], v111 offset:128
	s_nop 1
	ds_read_b128 v[88:91], v111 offset:192
	v_mfma_f32_16x16x32_bf16 v[84:87], v[80:83], v[4:7], v[84:87]
	v_mfma_f32_16x16x32_bf16 v[120:123], v[68:71], v[20:23], v[120:123]
	v_mfma_f32_16x16x32_bf16 v[124:127], v[80:83], v[20:23], v[124:127]
	v_mfma_f32_16x16x32_bf16 v[136:139], v[68:71], v[36:39], v[136:139]
	v_mfma_f32_16x16x32_bf16 v[140:143], v[80:83], v[36:39], v[140:143]
	v_mfma_f32_16x16x32_bf16 v[152:155], v[68:71], v[52:55], v[64:67]
	v_mfma_f32_16x16x32_bf16 v[76:79], v[80:83], v[52:55], v[76:79]
	s_waitcnt lgkmcnt(1)
	v_mfma_f32_16x16x32_bf16 v[164:167], v[92:95], v[8:11], v[72:75]
	s_nop 2
	ds_read_b128 v[72:75], v111 offset:4480
	ds_read_b128 v[80:83], v111 offset:4544
	ds_read_b128 v[172:175], v111 offset:8832
	ds_read_b128 v[68:71], v111 offset:8896
	ds_read_b128 v[180:183], v111 offset:13184
	ds_read_b128 v[64:67], v111 offset:13248
	s_waitcnt lgkmcnt(5)
	v_mfma_f32_16x16x32_bf16 v[168:171], v[72:75], v[8:11], v[84:87]
	v_lshl_add_u64 v[110:111], v[108:109], 2, s[20:21]
	s_nop 0
	v_mfma_f32_16x16x32_bf16 v[84:87], v[72:75], v[56:59], v[76:79]
	s_waitcnt lgkmcnt(3)
	v_mfma_f32_16x16x32_bf16 v[76:79], v[172:175], v[56:59], v[156:159]
	s_nop 2
	v_lshlrev_b64 v[156:157], 12, v[112:113]
	v_or_b32_e32 v156, v156, v115
	v_lshl_add_u64 v[158:159], s[26:27], 0, v[156:157]
	v_mfma_f32_16x16x32_bf16 v[120:123], v[92:95], v[24:27], v[120:123]
	v_mfma_f32_16x16x32_bf16 v[136:139], v[92:95], v[40:43], v[136:139]
	v_mfma_f32_16x16x32_bf16 v[92:95], v[92:95], v[56:59], v[152:155]
	s_nop 2
	s_nop 0
	v_mfma_f32_16x16x32_bf16 v[116:119], v[100:103], v[0:3], 0
	v_mfma_f32_16x16x32_bf16 v[132:135], v[100:103], v[16:19], 0
	v_mfma_f32_16x16x32_bf16 v[148:151], v[100:103], v[32:35], 0
	v_mfma_f32_16x16x32_bf16 v[100:103], v[100:103], v[48:51], 0
	v_mfma_f32_16x16x32_bf16 v[116:119], v[104:107], v[4:7], v[116:119]
	v_mfma_f32_16x16x32_bf16 v[132:135], v[104:107], v[20:23], v[132:135]
	v_mfma_f32_16x16x32_bf16 v[148:151], v[104:107], v[36:39], v[148:151]
	v_mfma_f32_16x16x32_bf16 v[160:163], v[104:107], v[52:55], v[100:103]
	v_mfma_f32_16x16x32_bf16 v[104:107], v[72:75], v[40:43], v[140:143]
	v_mfma_f32_16x16x32_bf16 v[140:143], v[88:91], v[12:15], v[164:167]
	v_mfma_f32_16x16x32_bf16 v[100:103], v[172:175], v[40:43], v[144:147]
	v_mfma_f32_16x16x32_bf16 v[144:147], v[80:83], v[12:15], v[168:171]
	s_waitcnt vmcnt(0)
	s_nop 1
	v_mov_b32_e32 v108, v216
	s_nop 4
	v_pk_add_f32 v[142:143], v[142:143], v[108:109] op_sel_hi:[1,0]
	v_mfma_f32_16x16x32_bf16 v[124:127], v[72:75], v[24:27], v[124:127]
	v_add_f32_e64 v140, v140, v108
	v_add_f32_e64 v141, v141, v108
	v_pk_add_f32 v[144:145], v[144:145], v[108:109] op_sel_hi:[1,0]
	v_pk_add_f32 v[146:147], v[146:147], v[108:109] op_sel_hi:[1,0]
	s_waitcnt lgkmcnt(1)
	v_mfma_f32_16x16x32_bf16 v[72:75], v[180:183], v[56:59], v[160:163]
	v_mfma_f32_16x16x32_bf16 v[176:179], v[172:175], v[8:11], v[96:99]
	s_nop 1
	v_mov_b32_e32 v152, v184
	v_mov_b32_e32 v153, v185
	v_mov_b32_e32 v154, v186
	v_mov_b32_e32 v155, v187
	s_nop 0
	v_lshlrev_b32_e32 v160, 16, v152
	v_and_b32_e32 v161, 0xffff0000, v152
	v_lshlrev_b32_e32 v152, 16, v153
	v_and_b32_e32 v153, 0xffff0000, v153
	v_pk_mul_f32 v[140:141], v[140:141], v[160:161]
	v_pk_mul_f32 v[142:143], v[142:143], v[152:153]
	v_cvt_pk_bf16_f32 v140, v140, v141
	v_cvt_pk_bf16_f32 v141, v142, v143
	v_lshlrev_b32_e32 v142, 16, v154
	v_and_b32_e32 v143, 0xffff0000, v154
	v_pk_mul_f32 v[142:143], v[144:145], v[142:143]
	v_lshlrev_b32_e32 v144, 16, v155
	v_and_b32_e32 v145, 0xffff0000, v155
	v_pk_mul_f32 v[144:145], v[146:147], v[144:145]
	v_cvt_pk_bf16_f32 v142, v142, v143
	v_cvt_pk_bf16_f32 v143, v144, v145
	v_lshl_add_u64 v[144:145], s[52:53], 0, v[156:157]
	global_store_dwordx4 v[144:145], v[140:143], off
	s_nop 0
	v_mfma_f32_16x16x32_bf16 v[116:119], v[180:183], v[8:11], v[116:119]
	v_mfma_f32_16x16x32_bf16 v[96:99], v[180:183], v[40:43], v[148:151]
	v_mfma_f32_16x16x32_bf16 v[148:151], v[68:71], v[12:15], v[176:179]
	s_waitcnt lgkmcnt(0)
; __device__ __forceinline__ unsigned pk2(float lo, float hi) { return cvt_pk_bf16(lo, hi); }
; __device__ __forceinline__ void unit(const Frame& F, int c, int g, const bf16x8 (&af)[4][4]) {
;     ...
; #pragma unroll
;     for (int m = 0; m < 4; ++m) {
;         const int p = wr * 64 + m * 16 + fr; const float bsp = F.b_sp[g * 128 + p];
;         const size_t rowoff = (size_t)(tok0 + p) * EA + ch0 + wc * 64 + 8 * fq;
; #pragma unroll
;         for (int h2 = 0; h2 < 2; ++h2) {
;             const u32x4 uu = *(const u32x4*)(F.U + rowoff + h2 * 32);
;             const f32x4 s0 = acc[m][2 * h2] + bsp, s1 = acc[m][2 * h2 + 1] + bsp;
;             u32x4 o;
;             o.x = pk2(bflo(uu.x) * s0[0], bfhi(uu.x) * s0[1]); o.y = pk2(bflo(uu.y) * s0[2], bfhi(uu.y) * s0[3]);
;             o.z = pk2(bflo(uu.z) * s1[0], bfhi(uu.z) * s1[1]); o.w = pk2(bflo(uu.w) * s1[2], bfhi(uu.w) * s1[3]);
;             *(u32x4*)(F.ABUF + rowoff + h2 * 32) = o;
;         }
	v_mfma_f32_16x16x32_bf16 v[116:119], v[64:67], v[12:15], v[116:119]
	v_mfma_f32_16x16x32_bf16 v[120:123], v[88:91], v[28:31], v[120:123]
	s_nop 4
	v_add_f32_e64 v146, v150, v108
	v_add_f32_e64 v147, v151, v108
	v_pk_add_f32 v[148:149], v[148:149], v[108:109] op_sel_hi:[1,0]
	v_pk_add_f32 v[150:151], v[118:119], v[108:109] op_sel_hi:[1,0]
	v_pk_add_f32 v[118:119], v[116:117], v[108:109] op_sel_hi:[1,0]
	v_mfma_f32_16x16x32_bf16 v[124:127], v[80:83], v[28:31], v[124:127]
	s_nop 1
	v_mov_b32_e32 v140, v188
	v_mov_b32_e32 v141, v189
	v_mov_b32_e32 v142, v190
	v_mov_b32_e32 v143, v191
	v_lshlrev_b32_e32 v116, 16, v140
	v_and_b32_e32 v117, 0xffff0000, v140
	v_lshlrev_b32_e32 v140, 16, v141
	v_and_b32_e32 v141, 0xffff0000, v141
	v_pk_mul_f32 v[116:117], v[148:149], v[116:117]
	v_pk_mul_f32 v[140:141], v[146:147], v[140:141]
	v_cvt_pk_bf16_f32 v116, v116, v117
	v_cvt_pk_bf16_f32 v117, v140, v141
	v_lshlrev_b32_e32 v140, 16, v142
	v_and_b32_e32 v141, 0xffff0000, v142
	v_pk_mul_f32 v[118:119], v[118:119], v[140:141]
	v_lshlrev_b32_e32 v140, 16, v143
	v_and_b32_e32 v141, 0xffff0000, v143
	v_pk_mul_f32 v[140:141], v[150:151], v[140:141]
	v_cvt_pk_bf16_f32 v118, v118, v119
	v_cvt_pk_bf16_f32 v119, v140, v141
	global_store_dwordx4 v[144:145], v[116:119], off offset:64
	s_nop 0
	v_mfma_f32_16x16x32_bf16 v[128:131], v[172:175], v[24:27], v[128:131]
	v_add_u32_e32 v116, 16, v112
	v_ashrrev_i32_e32 v117, 31, v116
	v_lshlrev_b64 v[140:141], 12, v[116:117]
	v_or_b32_e32 v140, v140, v115
	v_lshl_add_u64 v[142:143], s[26:27], 0, v[140:141]
	s_nop 0
	v_mfma_f32_16x16x32_bf16 v[132:135], v[180:183], v[24:27], v[132:135]
	s_nop 1
	v_mov_b32_e32 v108, v217
	v_pk_add_f32 v[120:121], v[120:121], v[108:109] op_sel_hi:[1,0]
	v_pk_add_f32 v[122:123], v[122:123], v[108:109] op_sel_hi:[1,0]
	v_pk_add_f32 v[124:125], v[124:125], v[108:109] op_sel_hi:[1,0]
	v_pk_add_f32 v[126:127], v[126:127], v[108:109] op_sel_hi:[1,0]
	v_mfma_f32_16x16x32_bf16 v[128:131], v[68:71], v[28:31], v[128:131]
	s_nop 1
	v_mov_b32_e32 v116, v192
	v_mov_b32_e32 v117, v193
	v_mov_b32_e32 v118, v194
	v_mov_b32_e32 v119, v195
	v_lshlrev_b32_e32 v144, 16, v116
	v_and_b32_e32 v145, 0xffff0000, v116
	v_pk_mul_f32 v[120:121], v[120:121], v[144:145]
	v_mfma_f32_16x16x32_bf16 v[132:135], v[64:67], v[28:31], v[132:135]
	v_cvt_pk_bf16_f32 v116, v120, v121
	v_lshlrev_b32_e32 v120, 16, v117
	v_and_b32_e32 v121, 0xffff0000, v117
	v_pk_mul_f32 v[120:121], v[122:123], v[120:121]
	v_pk_add_f32 v[128:129], v[128:129], v[108:109] op_sel_hi:[1,0]
	v_cvt_pk_bf16_f32 v117, v120, v121
	v_lshlrev_b32_e32 v120, 16, v118
	v_and_b32_e32 v121, 0xffff0000, v118
	v_pk_mul_f32 v[120:121], v[124:125], v[120:121]
	v_lshl_add_u64 v[124:125], s[52:53], 0, v[140:141]
	v_cvt_pk_bf16_f32 v118, v120, v121
	v_lshlrev_b32_e32 v120, 16, v119
	v_and_b32_e32 v121, 0xffff0000, v119
	v_pk_mul_f32 v[120:121], v[126:127], v[120:121]
	v_pk_add_f32 v[126:127], v[130:131], v[108:109] op_sel_hi:[1,0]
	v_cvt_pk_bf16_f32 v119, v120, v121
	global_store_dwordx4 v[124:125], v[116:119], off
	s_nop 0
	v_pk_add_f32 v[130:131], v[134:135], v[108:109] op_sel_hi:[1,0]
	v_pk_add_f32 v[132:133], v[132:133], v[108:109] op_sel_hi:[1,0]
	v_mfma_f32_16x16x32_bf16 v[120:123], v[88:91], v[44:47], v[136:139]
	s_nop 1
	v_mov_b32_e32 v116, v196
	v_mov_b32_e32 v117, v197
	v_mov_b32_e32 v118, v198
	v_mov_b32_e32 v119, v199
	v_lshlrev_b32_e32 v134, 16, v116
	v_and_b32_e32 v135, 0xffff0000, v116
	v_pk_mul_f32 v[128:129], v[128:129], v[134:135]
	v_mfma_f32_16x16x32_bf16 v[104:107], v[80:83], v[44:47], v[104:107]
	v_cvt_pk_bf16_f32 v116, v128, v129
	v_lshlrev_b32_e32 v128, 16, v117
	v_and_b32_e32 v129, 0xffff0000, v117
	v_pk_mul_f32 v[126:127], v[126:127], v[128:129]
	v_mfma_f32_16x16x32_bf16 v[100:103], v[68:71], v[44:47], v[100:103]
	v_cvt_pk_bf16_f32 v117, v126, v127
	v_lshlrev_b32_e32 v126, 16, v118
	v_and_b32_e32 v127, 0xffff0000, v118
	v_pk_mul_f32 v[126:127], v[132:133], v[126:127]
	v_mfma_f32_16x16x32_bf16 v[96:99], v[64:67], v[44:47], v[96:99]
	v_cvt_pk_bf16_f32 v118, v126, v127
	v_lshlrev_b32_e32 v126, 16, v119
	v_and_b32_e32 v127, 0xffff0000, v119
	v_pk_mul_f32 v[126:127], v[130:131], v[126:127]
	v_mfma_f32_16x16x32_bf16 v[88:91], v[88:91], v[60:63], v[92:95]
	v_cvt_pk_bf16_f32 v119, v126, v127
	global_store_dwordx4 v[124:125], v[116:119], off offset:64
	s_nop 0
	v_mfma_f32_16x16x32_bf16 v[80:83], v[80:83], v[60:63], v[84:87]
	v_add_u32_e32 v116, 32, v112
	v_ashrrev_i32_e32 v117, 31, v116
	v_lshlrev_b64 v[124:125], 12, v[116:117]
	v_or_b32_e32 v124, v124, v115
	v_lshl_add_u64 v[126:127], s[26:27], 0, v[124:125]
	s_nop 0
; __device__ __forceinline__ unsigned pk2(float lo, float hi) { return cvt_pk_bf16(lo, hi); }
; __device__ __forceinline__ void unit(const Frame& F, int c, int g, const bf16x8 (&af)[4][4]) {
;     ...
; #pragma unroll
;     for (int m = 0; m < 4; ++m) {
;         const int p = wr * 64 + m * 16 + fr; const float bsp = F.b_sp[g * 128 + p];
;         const size_t rowoff = (size_t)(tok0 + p) * EA + ch0 + wc * 64 + 8 * fq;
; #pragma unroll
;         for (int h2 = 0; h2 < 2; ++h2) {
;             const u32x4 uu = *(const u32x4*)(F.U + rowoff + h2 * 32);
;             const f32x4 s0 = acc[m][2 * h2] + bsp, s1 = acc[m][2 * h2 + 1] + bsp;
;             u32x4 o;
;             o.x = pk2(bflo(uu.x) * s0[0], bfhi(uu.x) * s0[1]); o.y = pk2(bflo(uu.y) * s0[2], bfhi(uu.y) * s0[3]);
;             o.z = pk2(bflo(uu.z) * s1[0], bfhi(uu.z) * s1[1]); o.w = pk2(bflo(uu.w) * s1[2], bfhi(uu.w) * s1[3]);
;             *(u32x4*)(F.ABUF + rowoff + h2 * 32) = o;
;         }
;     }
;     __syncthreads();
	v_lshl_add_u64 v[124:125], s[52:53], 0, v[124:125]
	v_add_u32_e32 v112, 48, v112
	v_ashrrev_i32_e32 v113, 31, v112
	v_lshlrev_b64 v[112:113], 12, v[112:113]
	v_or_b32_e32 v112, v112, v115
	v_mfma_f32_16x16x32_bf16 v[68:71], v[68:71], v[60:63], v[76:79]
	s_nop 1
	v_mov_b32_e32 v108, v218
	v_pk_add_f32 v[122:123], v[122:123], v[108:109] op_sel_hi:[1,0]
	v_pk_add_f32 v[120:121], v[120:121], v[108:109] op_sel_hi:[1,0]
	v_pk_add_f32 v[106:107], v[106:107], v[108:109] op_sel_hi:[1,0]
	v_pk_add_f32 v[104:105], v[104:105], v[108:109] op_sel_hi:[1,0]
	v_pk_add_f32 v[102:103], v[102:103], v[108:109] op_sel_hi:[1,0]
	v_pk_add_f32 v[100:101], v[100:101], v[108:109] op_sel_hi:[1,0]
	v_pk_add_f32 v[98:99], v[98:99], v[108:109] op_sel_hi:[1,0]
	s_nop 1
	v_mov_b32_e32 v116, v200
	v_mov_b32_e32 v117, v201
	v_mov_b32_e32 v118, v202
	v_mov_b32_e32 v119, v203
	v_lshlrev_b32_e32 v128, 16, v116
	v_and_b32_e32 v129, 0xffff0000, v116
	v_lshlrev_b32_e32 v116, 16, v117
	v_and_b32_e32 v117, 0xffff0000, v117
	v_lshlrev_b32_e32 v130, 16, v118
	v_and_b32_e32 v131, 0xffff0000, v118
	v_lshlrev_b32_e32 v118, 16, v119
	v_and_b32_e32 v119, 0xffff0000, v119
	v_pk_mul_f32 v[120:121], v[120:121], v[128:129]
	v_pk_mul_f32 v[116:117], v[122:123], v[116:117]
	v_pk_mul_f32 v[122:123], v[104:105], v[130:131]
	v_pk_mul_f32 v[118:119], v[106:107], v[118:119]
	v_cvt_pk_bf16_f32 v104, v120, v121
	v_cvt_pk_bf16_f32 v105, v116, v117
	v_cvt_pk_bf16_f32 v106, v122, v123
	v_cvt_pk_bf16_f32 v107, v118, v119
	global_store_dwordx4 v[124:125], v[104:107], off
	s_nop 0
	v_pk_add_f32 v[96:97], v[96:97], v[108:109] op_sel_hi:[1,0]
	v_mfma_f32_16x16x32_bf16 v[64:67], v[64:67], v[60:63], v[72:75]
	s_nop 1
	v_mov_b32_e32 v104, v204
	v_mov_b32_e32 v105, v205
	v_mov_b32_e32 v106, v206
	v_mov_b32_e32 v107, v207
	v_lshlrev_b32_e32 v116, 16, v104
	v_and_b32_e32 v117, 0xffff0000, v104
	v_lshlrev_b32_e32 v104, 16, v105
	v_and_b32_e32 v105, 0xffff0000, v105
	v_lshlrev_b32_e32 v118, 16, v106
	v_and_b32_e32 v119, 0xffff0000, v106
	v_lshlrev_b32_e32 v106, 16, v107
	v_and_b32_e32 v107, 0xffff0000, v107
	v_pk_mul_f32 v[100:101], v[100:101], v[116:117]
	v_pk_mul_f32 v[102:103], v[102:103], v[104:105]
	v_pk_mul_f32 v[104:105], v[96:97], v[118:119]
	v_pk_mul_f32 v[106:107], v[98:99], v[106:107]
	v_cvt_pk_bf16_f32 v96, v100, v101
	v_cvt_pk_bf16_f32 v97, v102, v103
	v_cvt_pk_bf16_f32 v98, v104, v105
	v_cvt_pk_bf16_f32 v99, v106, v107
	global_store_dwordx4 v[124:125], v[96:99], off offset:64
	s_nop 0
	v_lshl_add_u64 v[100:101], s[52:53], 0, v[112:113]
	v_lshl_add_u64 v[98:99], s[26:27], 0, v[112:113]
	s_nop 0
	s_nop 1
	v_mov_b32_e32 v96, v219
	v_pk_add_f32 v[84:85], v[90:91], v[96:97] op_sel_hi:[1,0]
	v_pk_add_f32 v[86:87], v[88:89], v[96:97] op_sel_hi:[1,0]
	v_pk_add_f32 v[82:83], v[82:83], v[96:97] op_sel_hi:[1,0]
	v_pk_add_f32 v[80:81], v[80:81], v[96:97] op_sel_hi:[1,0]
	s_nop 1
	v_mov_b32_e32 v92, v208
	v_mov_b32_e32 v93, v209
	v_mov_b32_e32 v94, v210
	v_mov_b32_e32 v95, v211
	v_lshlrev_b32_e32 v88, 16, v92
	v_and_b32_e32 v89, 0xffff0000, v92
	v_lshlrev_b32_e32 v90, 16, v93
	v_and_b32_e32 v91, 0xffff0000, v93
	v_lshlrev_b32_e32 v92, 16, v94
	v_and_b32_e32 v93, 0xffff0000, v94
	v_lshlrev_b32_e32 v94, 16, v95
	v_and_b32_e32 v95, 0xffff0000, v95
	v_pk_mul_f32 v[86:87], v[86:87], v[88:89]
	v_pk_mul_f32 v[84:85], v[84:85], v[90:91]
	v_pk_mul_f32 v[88:89], v[80:81], v[92:93]
	v_pk_mul_f32 v[90:91], v[82:83], v[94:95]
	v_cvt_pk_bf16_f32 v80, v86, v87
	v_cvt_pk_bf16_f32 v81, v84, v85
	v_cvt_pk_bf16_f32 v82, v88, v89
	v_cvt_pk_bf16_f32 v83, v90, v91
	global_store_dwordx4 v[100:101], v[80:83], off
	s_nop 0
	v_pk_add_f32 v[70:71], v[70:71], v[96:97] op_sel_hi:[1,0]
	v_pk_add_f32 v[68:69], v[68:69], v[96:97] op_sel_hi:[1,0]
	v_pk_add_f32 v[66:67], v[66:67], v[96:97] op_sel_hi:[1,0]
	v_pk_add_f32 v[64:65], v[64:65], v[96:97] op_sel_hi:[1,0]
	s_nop 1
	v_mov_b32_e32 v80, v212
	v_mov_b32_e32 v81, v213
	v_mov_b32_e32 v82, v214
	v_mov_b32_e32 v83, v215
	v_lshlrev_b32_e32 v72, 16, v80
	v_and_b32_e32 v73, 0xffff0000, v80
	v_lshlrev_b32_e32 v74, 16, v81
	v_and_b32_e32 v75, 0xffff0000, v81
	v_lshlrev_b32_e32 v76, 16, v82
	v_and_b32_e32 v77, 0xffff0000, v82
	v_lshlrev_b32_e32 v78, 16, v83
	v_and_b32_e32 v79, 0xffff0000, v83
	v_pk_mul_f32 v[68:69], v[68:69], v[72:73]
	v_pk_mul_f32 v[70:71], v[70:71], v[74:75]
	v_pk_mul_f32 v[72:73], v[64:65], v[76:77]
	v_pk_mul_f32 v[74:75], v[66:67], v[78:79]
	v_cvt_pk_bf16_f32 v64, v68, v69
	v_cvt_pk_bf16_f32 v65, v70, v71
	v_cvt_pk_bf16_f32 v66, v72, v73
	v_cvt_pk_bf16_f32 v67, v74, v75
	global_store_dwordx4 v[100:101], v[64:67], off offset:64
	s_barrier
	s_cbranch_scc0 .LBB0_310

; __device__ __forceinline__ void unit(const Frame& F, int c, int g, const bf16x8 (&af)[4][4]) {
;     ...
;     { const int row = tid >> 2, q = tid & 3; const f32x2* sp = F.VSTAT + (size_t)(q * 8) * M + tok0 + row;
;       float s = 0.f, ss = 0.f;
; #pragma unroll
;       for (int i = 0; i < 8; ++i) { const f32x2 v = sp[(size_t)i * M]; s += v[0]; ss += v[1]; }
;       s += __shfl_xor(s, 1); s += __shfl_xor(s, 2); ss += __shfl_xor(ss, 1); ss += __shfl_xor(ss, 2);
;       const float mean = s * (1.f / EA), var = ss * (1.f / EA) - mean * mean;
;       if (q == 0) ST[row] = (f32x2){mean, __builtin_amdgcn_rsqf(var + LN_EPS)}; }
;     __syncthreads();
; #pragma unroll
;     for (int cc = 0; cc < 4; ++cc) {
;         const int chunk = w * 4 + cc, r0 = 2 * lane;
;         const u32x4 x0 = *(const u32x4*)(F.V + (size_t)(tok0 + r0) * EA + ch0 + chunk * 8), x1 = *(const u32x4*)(F.V + (size_t)(tok0 + r0 + 1) * EA + ch0 + chunk * 8);
;         const f32x2 s0 = ST[r0], s1 = ST[r0 + 1];
;         const f32x4 ga = *(const f32x4*)(F.lnv_g + ch0 + chunk * 8), gb = *(const f32x4*)(F.lnv_g + ch0 + chunk * 8 + 4);
;         const f32x4 ba = *(const f32x4*)(F.lnv_b + ch0 + chunk * 8), bb = *(const f32x4*)(F.lnv_b + ch0 + chunk * 8 + 4);
.LBB0_308:
	v_mbcnt_lo_u32_b32 v64, -1, 0
	v_mbcnt_hi_u32_b32 v64, -1, v64
	s_and_b32 s60, s35, 0xffffff80
	v_add_u32_e32 v110, s74, v64
	v_and_b32_e32 v229, 63, v110
	v_lshl_or_b32 v230, v229, 1, s60
	v_ashrrev_i32_e32 v231, 31, v230
	s_and_b32 s98, s72, 7
	s_lshl_b32 s100, s98, 9
	s_mov_b32 s101, s7
	s_lshl_b32 s99, s98, 10
	v_lshlrev_b64 v[232:233], 12, v[230:231]
	v_lshl_add_u64 v[232:233], s[76:77], 0, v[232:233]
	v_lshl_add_u64 v[232:233], v[232:233], 0, s[100:101]
	v_mov_b32_e32 v236, s99
	v_lshl_add_u64 v[234:235], v[232:233], 0, s[58:59]
	v_or_b32_e32 v230, 1, v230
	v_ashrrev_i32_e32 v231, 31, v230
	v_lshlrev_b64 v[238:239], 12, v[230:231]
	v_lshl_add_u64 v[238:239], s[76:77], 0, v[238:239]
	v_lshl_add_u64 v[238:239], v[238:239], 0, s[100:101]
	v_lshl_add_u64 v[238:239], v[238:239], 0, s[58:59]
	global_load_dwordx4 v[104:107], v236, s[8:9]
	global_load_dwordx4 v[116:119], v236, s[22:23]
	global_load_dwordx4 v[120:123], v[234:235], off
	global_load_dwordx4 v[124:127], v[238:239], off
	global_load_dwordx4 v[128:131], v236, s[8:9] offset:16
	global_load_dwordx4 v[132:135], v236, s[22:23] offset:16
	global_load_dwordx4 v[80:83], v[234:235], off offset:16
	global_load_dwordx4 v[84:87], v[238:239], off offset:16
	global_load_dwordx4 v[88:91], v236, s[8:9] offset:48
	global_load_dwordx4 v[96:99], v236, s[8:9] offset:32
	global_load_dwordx4 v[92:95], v236, s[22:23] offset:48
	global_load_dwordx4 v[100:103], v236, s[22:23] offset:32
	s_ashr_i32 s61, s60, 31
	v_and_b32_e32 v240, 3, v110
	v_mul_u32_u24_e32 v65, 0x30000, v240
	v_lshlrev_b32_e32 v108, 3, v65
	v_ashrrev_i32_e32 v64, 2, v110
	v_lshl_add_u64 v[66:67], s[78:79], 0, v[108:109]
	v_lshl_add_u64 v[66:67], s[60:61], 3, v[66:67]
	v_ashrrev_i32_e32 v65, 31, v64
	v_lshl_add_u64 v[66:67], v[64:65], 3, v[66:67]
	v_add_co_u32_e32 v68, vcc, s65, v66
	v_and_b32_e32 v241, 64, v114
	s_nop 0
	v_addc_co_u32_e32 v69, vcc, 0, v67, vcc
	v_add_co_u32_e32 v70, vcc, s66, v66
	v_xor_b32_e32 v65, 1, v114
	s_nop 0
	v_addc_co_u32_e32 v71, vcc, 0, v67, vcc
	v_add_co_u32_e32 v72, vcc, s67, v66
	v_add_u32_e32 v241, 64, v241
	s_nop 0
	v_addc_co_u32_e32 v73, vcc, 0, v67, vcc
	v_add_co_u32_e32 v76, vcc, s68, v66
	s_nop 1
	v_addc_co_u32_e32 v77, vcc, 0, v67, vcc
	v_add_co_u32_e32 v78, vcc, s69, v66
	s_nop 1
	v_addc_co_u32_e32 v79, vcc, 0, v67, vcc
	v_add_co_u32_e32 v242, vcc, s70, v66
	s_nop 1
	v_addc_co_u32_e32 v243, vcc, 0, v67, vcc
	global_load_dwordx2 v[74:75], v[66:67], off
	s_nop 0
	global_load_dwordx2 v[68:69], v[68:69], off
	s_nop 0
	global_load_dwordx2 v[70:71], v[70:71], off
	s_nop 0
	global_load_dwordx2 v[72:73], v[72:73], off
	s_nop 0
	global_load_dwordx2 v[76:77], v[76:77], off
	s_nop 0
	global_load_dwordx2 v[78:79], v[78:79], off
	s_nop 0
	global_load_dwordx2 v[242:243], v[242:243], off
	v_add_co_u32_e32 v66, vcc, s71, v66
	s_nop 1
	v_addc_co_u32_e32 v67, vcc, 0, v67, vcc
	s_nop 0
	global_load_dwordx2 v[66:67], v[66:67], off
	s_waitcnt vmcnt(7)
	v_pk_add_f32 v[74:75], v[74:75], 0 op_sel_hi:[1,0]
	s_waitcnt vmcnt(6)
	v_pk_add_f32 v[68:69], v[74:75], v[68:69]
	s_waitcnt vmcnt(5)
	v_pk_add_f32 v[68:69], v[68:69], v[70:71]
	s_waitcnt vmcnt(4)
	v_pk_add_f32 v[68:69], v[68:69], v[72:73]
	v_cmp_lt_i32_e32 vcc, v65, v241
	s_waitcnt vmcnt(3)
	v_pk_add_f32 v[68:69], v[68:69], v[76:77]
	s_waitcnt vmcnt(2)
	v_pk_add_f32 v[68:69], v[68:69], v[78:79]
	v_cndmask_b32_e32 v65, v114, v65, vcc
	s_waitcnt vmcnt(1)
	v_pk_add_f32 v[68:69], v[68:69], v[242:243]
	v_lshlrev_b32_e32 v65, 2, v65
	s_waitcnt vmcnt(0)
	v_pk_add_f32 v[66:67], v[68:69], v[66:67]
	ds_bpermute_b32 v68, v65, v66
	ds_bpermute_b32 v69, v65, v67
	v_xor_b32_e32 v65, 2, v114
	v_cmp_lt_i32_e32 vcc, v65, v241
	s_waitcnt lgkmcnt(0)
	v_pk_add_f32 v[66:67], v[66:67], v[68:69]
	v_cndmask_b32_e32 v65, v114, v65, vcc
	v_lshlrev_b32_e32 v65, 2, v65
	ds_bpermute_b32 v68, v65, v66
	ds_bpermute_b32 v69, v65, v67
	v_cmp_eq_u32_e32 vcc, 0, v240
	s_and_saveexec_b64 s[62:63], vcc
	s_cbranch_execz .LBB0_305
	s_waitcnt lgkmcnt(0)
	v_pk_add_f32 v[66:67], v[66:67], v[68:69]
	v_lshl_add_u32 v64, v64, 3, 0
	v_pk_mul_f32 v[66:67], v[66:67], s[24:25] op_sel_hi:[1,0]
	v_add_u32_e32 v64, 0x11000, v64
	v_fma_f32 v65, -v66, v66, v67
	v_add_f32_e32 v65, 0x3727c5ac, v65
	v_rsq_f32_e32 v67, v65
	ds_write_b64 v64, v[66:67]
	s_branch .LBB0_305
